# final rmsnorm: final_norm vectors kept in registers so result stores no longer serialize behind vmcnt(0)
# baseline (speedup 1.0000x reference)
.LBB0_684:
	global_load_dwordx4 v[152:155], v[116:117], off
	global_load_dwordx4 v[156:159], v[116:117], off offset:1024
	global_load_dwordx4 v[160:163], v[116:117], off offset:2048
	global_load_dwordx4 v[164:167], v[116:117], off offset:3072
	v_add_u32_e32 v122, s21, v112
	v_cmp_gt_i32_e32 vcc, s9, v122
	v_ashrrev_i32_e32 v113, 31, v112
	v_lshlrev_b64 v[0:1], 5, v[112:113]
	v_cndmask_b32_e32 v16, v112, v122, vcc
	v_lshl_add_u64 v[8:9], s[16:17], 0, v[0:1]
	v_ashrrev_i32_e32 v17, 31, v16
	global_load_dwordx4 v[0:3], v[8:9], off offset:16
	global_load_dwordx4 v[4:7], v[8:9], off
	v_lshlrev_b64 v[8:9], 5, v[16:17]
	v_lshl_add_u64 v[18:19], s[16:17], 0, v[8:9]
	global_load_dwordx4 v[8:11], v[18:19], off
	global_load_dwordx4 v[12:15], v[18:19], off offset:16
	v_lshlrev_b64 v[142:143], 12, v[112:113]
	v_lshl_add_u64 v[146:147], v[114:115], 0, v[142:143]
	global_load_dwordx4 v[138:141], v[146:147], off
	global_load_dwordx4 v[134:137], v[116:117], off
	v_add_u32_e32 v130, s12, v112
	v_add_u32_e32 v128, s19, v112
	v_cmp_gt_i32_e32 vcc, s9, v130
	v_add_u32_e32 v132, s18, v112
	v_add_u32_e32 v124, s13, v112
	v_cndmask_b32_e32 v20, v112, v130, vcc
	v_cmp_gt_i32_e32 vcc, s9, v128
	v_cmp_gt_i32_e64 s[0:1], s9, v132
	v_ashrrev_i32_e32 v21, 31, v20
	v_cndmask_b32_e32 v22, v112, v128, vcc
	v_cmp_gt_i32_e32 vcc, s9, v124
	v_cndmask_b32_e64 v18, v112, v132, s[0:1]
	v_ashrrev_i32_e32 v19, 31, v18
	v_cndmask_b32_e32 v24, v112, v124, vcc
	v_ashrrev_i32_e32 v23, 31, v22
	v_ashrrev_i32_e32 v25, 31, v24
	v_lshlrev_b64 v[26:27], 5, v[18:19]
	v_lshlrev_b64 v[18:19], 12, v[18:19]
	v_lshlrev_b64 v[28:29], 5, v[20:21]
	v_lshlrev_b64 v[20:21], 12, v[20:21]
	v_lshlrev_b64 v[30:31], 5, v[22:23]
	v_lshlrev_b64 v[22:23], 12, v[22:23]
	v_lshlrev_b64 v[32:33], 5, v[24:25]
	v_lshlrev_b64 v[24:25], 12, v[24:25]
	v_lshlrev_b64 v[16:17], 12, v[16:17]
	v_lshl_add_u64 v[26:27], s[16:17], 0, v[26:27]
	v_lshl_add_u64 v[18:19], v[114:115], 0, v[18:19]
	v_lshl_add_u64 v[28:29], s[16:17], 0, v[28:29]
	v_lshl_add_u64 v[20:21], v[114:115], 0, v[20:21]
	v_lshl_add_u64 v[30:31], s[16:17], 0, v[30:31]
	v_lshl_add_u64 v[22:23], v[114:115], 0, v[22:23]
	v_lshl_add_u64 v[56:57], s[16:17], 0, v[32:33]
	v_lshl_add_u64 v[126:127], v[114:115], 0, v[24:25]
	v_lshl_add_u64 v[144:145], v[114:115], 0, v[16:17]
	global_load_dwordx4 v[104:107], v[26:27], off offset:16
	global_load_dwordx4 v[108:111], v[26:27], off
	global_load_dwordx4 v[100:103], v[18:19], off
	global_load_dwordx4 v[96:99], v[18:19], off offset:1024
	global_load_dwordx4 v[92:95], v[18:19], off offset:2048
	global_load_dwordx4 v[88:91], v[18:19], off offset:3072
	global_load_dwordx4 v[80:83], v[28:29], off offset:16
	global_load_dwordx4 v[84:87], v[28:29], off
	global_load_dwordx4 v[76:79], v[20:21], off
	global_load_dwordx4 v[72:75], v[20:21], off offset:1024
	global_load_dwordx4 v[68:71], v[20:21], off offset:2048
	global_load_dwordx4 v[64:67], v[20:21], off offset:3072
	global_load_dwordx4 v[52:55], v[30:31], off offset:16
	global_load_dwordx4 v[60:63], v[30:31], off
	global_load_dwordx4 v[44:47], v[22:23], off
	global_load_dwordx4 v[40:43], v[22:23], off offset:1024
	global_load_dwordx4 v[36:39], v[22:23], off offset:2048
	global_load_dwordx4 v[32:35], v[22:23], off offset:3072
	global_load_dwordx4 v[48:51], v[56:57], off offset:16
	s_nop 0
	global_load_dwordx4 v[56:59], v[56:57], off
	s_nop 0
	global_load_dwordx4 v[28:31], v[126:127], off
	global_load_dwordx4 v[24:27], v[126:127], off offset:1024
	global_load_dwordx4 v[20:23], v[126:127], off offset:2048
	global_load_dwordx4 v[16:19], v[126:127], off offset:3072
	v_lshl_add_u64 v[150:151], v[118:119], 0, v[142:143]
	s_waitcnt vmcnt(29)
	v_mov_b32_e32 v127, v0
	s_waitcnt vmcnt(28)
	v_mov_b32_e32 v126, v4
	v_mov_b32_e32 v0, v5
	s_waitcnt vmcnt(27)
	v_mov_b32_e32 v4, v8
	s_waitcnt vmcnt(26)
	v_mov_b32_e32 v5, v12
	v_mov_b32_e32 v12, v9
	v_mov_b32_e32 v8, v10
	v_mov_b32_e32 v9, v14
	v_mov_b32_e32 v14, v11
	v_pk_add_f32 v[4:5], v[4:5], v[12:13]
	v_pk_add_f32 v[8:9], v[8:9], v[14:15]
	v_pk_add_f32 v[0:1], v[126:127], v[0:1]
	v_pk_add_f32 v[4:5], v[4:5], v[8:9]
	v_mov_b32_e32 v8, v6
	v_mov_b32_e32 v9, v2
	v_mov_b32_e32 v2, v7
	v_pk_add_f32 v[2:3], v[8:9], v[2:3]
	s_nop 0
	v_pk_add_f32 v[0:1], v[0:1], v[2:3]
	v_mov_b32_e32 v3, v4
	v_mov_b32_e32 v2, v0
	v_mov_b32_e32 v4, v1
	v_pk_add_f32 v[0:1], v[2:3], v[4:5]
	s_nop 0
	v_pk_fma_f32 v[126:127], v[0:1], s[8:9], v[120:121] op_sel_hi:[1,0,0]
	s_nop 0
	v_mul_f32_e32 v0, 0x4b800000, v126
	v_cmp_gt_f32_e32 vcc, s14, v126
	s_nop 1
	v_cndmask_b32_e32 v0, v126, v0, vcc
	v_rsq_f32_e32 v113, v0
	global_load_dwordx4 v[12:15], v[144:145], off
	global_load_dwordx4 v[8:11], v[144:145], off offset:1024
	global_load_dwordx4 v[4:7], v[144:145], off offset:2048
	global_load_dwordx4 v[0:3], v[144:145], off offset:3072
	v_mul_f32_e32 v121, 0x45800000, v113
	v_cndmask_b32_e32 v126, v113, v121, vcc
	s_waitcnt vmcnt(29)
	v_pk_mul_f32 v[138:139], v[138:139], v[126:127] op_sel_hi:[1,0]
	global_load_dwordx4 v[142:145], v[146:147], off offset:1024
	s_waitcnt vmcnt(29)
	v_pk_mul_f32 v[134:135], v[134:135], v[138:139]
	v_pk_mul_f32 v[138:139], v[140:141], v[126:127] op_sel_hi:[1,0]
	v_cmp_gt_f32_e32 vcc, s14, v127
	v_pk_mul_f32 v[136:137], v[136:137], v[138:139]
	global_load_dwordx4 v[138:141], v[146:147], off offset:2048
	s_nop 0
	global_load_dwordx4 v[146:149], v[146:147], off offset:3072
	s_waitcnt vmcnt(2)
	v_pk_mul_f32 v[142:143], v[142:143], v[126:127] op_sel_hi:[1,0]
	global_store_dwordx4 v[150:151], v[134:137], off
	s_nop 1
	v_mov_b64_e32 v[134:135], v[156:157]
	v_mov_b64_e32 v[136:137], v[158:159]
	v_pk_mul_f32 v[144:145], v[144:145], v[126:127] op_sel_hi:[1,0]
	s_waitcnt vmcnt(2)
	v_pk_mul_f32 v[138:139], v[138:139], v[126:127] op_sel_hi:[1,0]
	v_pk_mul_f32 v[140:141], v[140:141], v[126:127] op_sel_hi:[1,0]
	v_pk_mul_f32 v[134:135], v[134:135], v[142:143]
	v_pk_mul_f32 v[136:137], v[136:137], v[144:145]
	global_store_dwordx4 v[150:151], v[134:137], off offset:1024
	s_nop 1
	v_mov_b64_e32 v[134:135], v[160:161]
	v_mov_b64_e32 v[136:137], v[162:163]
	v_pk_mul_f32 v[134:135], v[134:135], v[138:139]
	v_pk_mul_f32 v[136:137], v[136:137], v[140:141]
	global_store_dwordx4 v[150:151], v[134:137], off offset:2048
	s_waitcnt vmcnt(3)
	s_nop 1
	v_mov_b64_e32 v[134:135], v[164:165]
	v_mov_b64_e32 v[136:137], v[166:167]
	v_pk_mul_f32 v[138:139], v[146:147], v[126:127] op_sel_hi:[1,0]
	v_pk_mul_f32 v[140:141], v[148:149], v[126:127] op_sel_hi:[1,0]
	v_pk_mul_f32 v[134:135], v[134:135], v[138:139]
	v_pk_mul_f32 v[136:137], v[136:137], v[140:141]
	global_store_dwordx4 v[150:151], v[134:137], off offset:3072
	s_and_saveexec_b64 s[2:3], s[0:1]
	s_cbranch_execz .LBB0_686
	s_nop 1
	v_mov_b64_e32 v[134:135], v[152:153]
	v_mov_b64_e32 v[136:137], v[154:155]
	v_mov_b32_e32 v138, v108
	v_mov_b32_e32 v139, v104
	v_mov_b32_e32 v104, v109
	v_mov_b32_e32 v108, v110
	v_mov_b32_e32 v109, v106
	v_mov_b32_e32 v106, v111
	v_pk_add_f32 v[104:105], v[138:139], v[104:105]
	v_pk_add_f32 v[106:107], v[108:109], v[106:107]
	v_ashrrev_i32_e32 v133, 31, v132
	v_pk_add_f32 v[104:105], v[104:105], v[106:107]
	s_nop 0
	v_add_f32_e32 v104, v104, v105
	v_fmamk_f32 v104, v104, 0x3a800000, v120
	v_mul_f32_e32 v105, 0x4b800000, v104
	v_cmp_gt_f32_e64 s[0:1], s14, v104
	s_nop 1
	v_cndmask_b32_e64 v104, v104, v105, s[0:1]
	v_rsq_f32_e32 v106, v104
	v_lshlrev_b64 v[104:105], 12, v[132:133]
	v_lshl_add_u64 v[104:105], v[118:119], 0, v[104:105]
	v_mul_f32_e32 v107, 0x45800000, v106
	v_cndmask_b32_e64 v106, v106, v107, s[0:1]
	v_pk_mul_f32 v[100:101], v[100:101], v[106:107] op_sel_hi:[1,0]
	v_pk_mul_f32 v[102:103], v[102:103], v[106:107] op_sel_hi:[1,0]
	v_pk_mul_f32 v[96:97], v[96:97], v[106:107] op_sel_hi:[1,0]
	v_pk_mul_f32 v[98:99], v[98:99], v[106:107] op_sel_hi:[1,0]
	v_pk_mul_f32 v[92:93], v[92:93], v[106:107] op_sel_hi:[1,0]
	v_pk_mul_f32 v[94:95], v[94:95], v[106:107] op_sel_hi:[1,0]
	v_pk_mul_f32 v[88:89], v[88:89], v[106:107] op_sel_hi:[1,0]
	v_pk_mul_f32 v[90:91], v[90:91], v[106:107] op_sel_hi:[1,0]
	v_pk_mul_f32 v[100:101], v[134:135], v[100:101]
	v_pk_mul_f32 v[102:103], v[136:137], v[102:103]
	global_store_dwordx4 v[104:105], v[100:103], off
	s_nop 1
	v_mov_b64_e32 v[100:101], v[156:157]
	v_mov_b64_e32 v[102:103], v[158:159]
	v_pk_mul_f32 v[96:97], v[100:101], v[96:97]
	v_pk_mul_f32 v[98:99], v[102:103], v[98:99]
	global_store_dwordx4 v[104:105], v[96:99], off offset:1024
	s_nop 1
	v_mov_b64_e32 v[96:97], v[160:161]
	v_mov_b64_e32 v[98:99], v[162:163]
	v_pk_mul_f32 v[92:93], v[96:97], v[92:93]
	v_pk_mul_f32 v[94:95], v[98:99], v[94:95]
	global_store_dwordx4 v[104:105], v[92:95], off offset:2048
	s_nop 1
	v_mov_b64_e32 v[92:93], v[164:165]
	v_mov_b64_e32 v[94:95], v[166:167]
	v_pk_mul_f32 v[88:89], v[92:93], v[88:89]
	v_pk_mul_f32 v[90:91], v[94:95], v[90:91]
	global_store_dwordx4 v[104:105], v[88:91], off offset:3072
.LBB0_686:
	s_or_b64 exec, exec, s[2:3]
	v_cmp_gt_i32_e64 s[0:1], s9, v130
	s_and_saveexec_b64 s[2:3], s[0:1]
	s_cbranch_execz .LBB0_688
	s_nop 1
	v_mov_b64_e32 v[88:89], v[152:153]
	v_mov_b64_e32 v[90:91], v[154:155]
	v_mov_b32_e32 v92, v84
	v_mov_b32_e32 v93, v80
	v_mov_b32_e32 v80, v85
	v_mov_b32_e32 v84, v86
	v_mov_b32_e32 v85, v82
	v_mov_b32_e32 v82, v87
	v_pk_add_f32 v[80:81], v[92:93], v[80:81]
	v_pk_add_f32 v[82:83], v[84:85], v[82:83]
	v_ashrrev_i32_e32 v131, 31, v130
	v_pk_add_f32 v[80:81], v[80:81], v[82:83]
	s_nop 0
	v_add_f32_e32 v80, v80, v81
	v_fmamk_f32 v80, v80, 0x3a800000, v120
	v_mul_f32_e32 v81, 0x4b800000, v80
	v_cmp_gt_f32_e64 s[0:1], s14, v80
	s_nop 1
	v_cndmask_b32_e64 v80, v80, v81, s[0:1]
	v_rsq_f32_e32 v82, v80
	v_lshlrev_b64 v[80:81], 12, v[130:131]
	v_lshl_add_u64 v[80:81], v[118:119], 0, v[80:81]
	v_mul_f32_e32 v83, 0x45800000, v82
	v_cndmask_b32_e64 v82, v82, v83, s[0:1]
	v_pk_mul_f32 v[76:77], v[76:77], v[82:83] op_sel_hi:[1,0]
	v_pk_mul_f32 v[78:79], v[78:79], v[82:83] op_sel_hi:[1,0]
	v_pk_mul_f32 v[72:73], v[72:73], v[82:83] op_sel_hi:[1,0]
	v_pk_mul_f32 v[74:75], v[74:75], v[82:83] op_sel_hi:[1,0]
	v_pk_mul_f32 v[68:69], v[68:69], v[82:83] op_sel_hi:[1,0]
	v_pk_mul_f32 v[70:71], v[70:71], v[82:83] op_sel_hi:[1,0]
	v_pk_mul_f32 v[64:65], v[64:65], v[82:83] op_sel_hi:[1,0]
	v_pk_mul_f32 v[66:67], v[66:67], v[82:83] op_sel_hi:[1,0]
	v_pk_mul_f32 v[76:77], v[88:89], v[76:77]
	v_pk_mul_f32 v[78:79], v[90:91], v[78:79]
	global_store_dwordx4 v[80:81], v[76:79], off
	s_nop 1
	v_mov_b64_e32 v[76:77], v[156:157]
	v_mov_b64_e32 v[78:79], v[158:159]
	v_pk_mul_f32 v[72:73], v[76:77], v[72:73]
	v_pk_mul_f32 v[74:75], v[78:79], v[74:75]
	global_store_dwordx4 v[80:81], v[72:75], off offset:1024
	s_nop 1
	v_mov_b64_e32 v[72:73], v[160:161]
	v_mov_b64_e32 v[74:75], v[162:163]
	v_pk_mul_f32 v[68:69], v[72:73], v[68:69]
	v_pk_mul_f32 v[70:71], v[74:75], v[70:71]
	global_store_dwordx4 v[80:81], v[68:71], off offset:2048
	s_nop 1
	v_mov_b64_e32 v[68:69], v[164:165]
	v_mov_b64_e32 v[70:71], v[166:167]
	v_pk_mul_f32 v[64:65], v[68:69], v[64:65]
	v_pk_mul_f32 v[66:67], v[70:71], v[66:67]
	global_store_dwordx4 v[80:81], v[64:67], off offset:3072

.LBB0_691:
	s_nop 1
	v_mov_b64_e32 v[50:51], v[152:153]
	v_mov_b64_e32 v[52:53], v[154:155]
	v_mul_f32_e32 v54, 0x4b800000, v49
	v_cndmask_b32_e64 v49, v49, v54, s[2:3]
	v_rsq_f32_e32 v49, v49
	v_ashrrev_i32_e32 v129, 31, v128
	v_lshlrev_b64 v[54:55], 12, v[128:129]
	v_lshl_add_u64 v[54:55], v[118:119], 0, v[54:55]
	v_mul_f32_e32 v56, 0x45800000, v49
	v_cndmask_b32_e64 v56, v49, v56, s[2:3]
	v_pk_mul_f32 v[44:45], v[44:45], v[56:57] op_sel_hi:[1,0]
	v_pk_mul_f32 v[46:47], v[46:47], v[56:57] op_sel_hi:[1,0]
	v_pk_mul_f32 v[40:41], v[40:41], v[56:57] op_sel_hi:[1,0]
	v_pk_mul_f32 v[42:43], v[42:43], v[56:57] op_sel_hi:[1,0]
	v_pk_mul_f32 v[36:37], v[36:37], v[56:57] op_sel_hi:[1,0]
	v_pk_mul_f32 v[38:39], v[38:39], v[56:57] op_sel_hi:[1,0]
	v_pk_mul_f32 v[32:33], v[32:33], v[56:57] op_sel_hi:[1,0]
	v_pk_mul_f32 v[34:35], v[34:35], v[56:57] op_sel_hi:[1,0]
	v_pk_mul_f32 v[44:45], v[50:51], v[44:45]
	v_pk_mul_f32 v[46:47], v[52:53], v[46:47]
	global_store_dwordx4 v[54:55], v[44:47], off
	s_nop 1
	v_mov_b64_e32 v[44:45], v[156:157]
	v_mov_b64_e32 v[46:47], v[158:159]
	v_pk_mul_f32 v[40:41], v[44:45], v[40:41]
	v_pk_mul_f32 v[42:43], v[46:47], v[42:43]
	global_store_dwordx4 v[54:55], v[40:43], off offset:1024
	s_nop 1
	v_mov_b64_e32 v[40:41], v[160:161]
	v_mov_b64_e32 v[42:43], v[162:163]
	v_pk_mul_f32 v[36:37], v[40:41], v[36:37]
	v_pk_mul_f32 v[38:39], v[42:43], v[38:39]
	global_store_dwordx4 v[54:55], v[36:39], off offset:2048
	s_nop 1
	v_mov_b64_e32 v[36:37], v[164:165]
	v_mov_b64_e32 v[38:39], v[166:167]
	v_pk_mul_f32 v[32:33], v[36:37], v[32:33]
	v_pk_mul_f32 v[34:35], v[38:39], v[34:35]
	global_store_dwordx4 v[54:55], v[32:35], off offset:3072
	s_or_b64 exec, exec, s[10:11]
	v_cmp_gt_i32_e64 s[2:3], s9, v124
	s_and_saveexec_b64 s[4:5], s[2:3]
	s_cbranch_execz .LBB0_690
.LBB0_692:
	s_nop 1
	v_mov_b64_e32 v[32:33], v[152:153]
	v_mov_b64_e32 v[34:35], v[154:155]
	v_mul_f32_e32 v36, 0x4b800000, v48
	v_cndmask_b32_e64 v36, v48, v36, s[0:1]
	v_rsq_f32_e32 v38, v36
	v_ashrrev_i32_e32 v125, 31, v124
	v_lshlrev_b64 v[36:37], 12, v[124:125]
	v_lshl_add_u64 v[36:37], v[118:119], 0, v[36:37]
	v_mul_f32_e32 v39, 0x45800000, v38
	v_cndmask_b32_e64 v38, v38, v39, s[0:1]
	v_pk_mul_f32 v[28:29], v[28:29], v[38:39] op_sel_hi:[1,0]
	v_pk_mul_f32 v[30:31], v[30:31], v[38:39] op_sel_hi:[1,0]
	v_pk_mul_f32 v[24:25], v[24:25], v[38:39] op_sel_hi:[1,0]
	v_pk_mul_f32 v[26:27], v[26:27], v[38:39] op_sel_hi:[1,0]
	v_pk_mul_f32 v[20:21], v[20:21], v[38:39] op_sel_hi:[1,0]
	v_pk_mul_f32 v[22:23], v[22:23], v[38:39] op_sel_hi:[1,0]
	v_pk_mul_f32 v[16:17], v[16:17], v[38:39] op_sel_hi:[1,0]
	v_pk_mul_f32 v[18:19], v[18:19], v[38:39] op_sel_hi:[1,0]
	v_pk_mul_f32 v[28:29], v[32:33], v[28:29]
	v_pk_mul_f32 v[30:31], v[34:35], v[30:31]
	global_store_dwordx4 v[36:37], v[28:31], off
	s_nop 1
	v_mov_b64_e32 v[28:29], v[156:157]
	v_mov_b64_e32 v[30:31], v[158:159]
	v_pk_mul_f32 v[24:25], v[28:29], v[24:25]
	v_pk_mul_f32 v[26:27], v[30:31], v[26:27]
	global_store_dwordx4 v[36:37], v[24:27], off offset:1024
	s_nop 1
	v_mov_b64_e32 v[24:25], v[160:161]
	v_mov_b64_e32 v[26:27], v[162:163]
	v_pk_mul_f32 v[20:21], v[24:25], v[20:21]
	v_pk_mul_f32 v[22:23], v[26:27], v[22:23]
	global_store_dwordx4 v[36:37], v[20:23], off offset:2048
	s_nop 1
	v_mov_b64_e32 v[20:21], v[164:165]
	v_mov_b64_e32 v[22:23], v[166:167]
	v_pk_mul_f32 v[16:17], v[20:21], v[16:17]
	v_pk_mul_f32 v[18:19], v[22:23], v[18:19]
	global_store_dwordx4 v[36:37], v[16:19], off offset:3072
	s_or_b64 exec, exec, s[4:5]
	v_cmp_gt_i32_e64 s[0:1], s9, v122
	s_and_saveexec_b64 s[2:3], s[0:1]
	s_cbranch_execz .LBB0_683
.LBB0_693:
	s_nop 1
	v_mov_b64_e32 v[16:17], v[152:153]
	v_mov_b64_e32 v[18:19], v[154:155]
	v_mul_f32_e32 v20, 0x4b800000, v127
	v_cndmask_b32_e32 v20, v127, v20, vcc
	v_rsq_f32_e32 v22, v20
	v_ashrrev_i32_e32 v123, 31, v122
	v_lshlrev_b64 v[20:21], 12, v[122:123]
	v_lshl_add_u64 v[20:21], v[118:119], 0, v[20:21]
	v_mul_f32_e32 v23, 0x45800000, v22
	v_cndmask_b32_e32 v22, v22, v23, vcc
	v_pk_mul_f32 v[12:13], v[12:13], v[22:23] op_sel_hi:[1,0]
	v_pk_mul_f32 v[14:15], v[14:15], v[22:23] op_sel_hi:[1,0]
	v_pk_mul_f32 v[8:9], v[8:9], v[22:23] op_sel_hi:[1,0]
	v_pk_mul_f32 v[10:11], v[10:11], v[22:23] op_sel_hi:[1,0]
	v_pk_mul_f32 v[4:5], v[4:5], v[22:23] op_sel_hi:[1,0]
	v_pk_mul_f32 v[6:7], v[6:7], v[22:23] op_sel_hi:[1,0]
	v_pk_mul_f32 v[0:1], v[0:1], v[22:23] op_sel_hi:[1,0]
	v_pk_mul_f32 v[2:3], v[2:3], v[22:23] op_sel_hi:[1,0]
	v_pk_mul_f32 v[12:13], v[16:17], v[12:13]
	v_pk_mul_f32 v[14:15], v[18:19], v[14:15]
	global_store_dwordx4 v[20:21], v[12:15], off
	s_nop 1
	v_mov_b64_e32 v[12:13], v[156:157]
	v_mov_b64_e32 v[14:15], v[158:159]
	v_pk_mul_f32 v[8:9], v[12:13], v[8:9]
	v_pk_mul_f32 v[10:11], v[14:15], v[10:11]
	global_store_dwordx4 v[20:21], v[8:11], off offset:1024
	s_nop 1
	v_mov_b64_e32 v[8:9], v[160:161]
	v_mov_b64_e32 v[10:11], v[162:163]
	v_pk_mul_f32 v[4:5], v[8:9], v[4:5]
	v_pk_mul_f32 v[6:7], v[10:11], v[6:7]
	global_store_dwordx4 v[20:21], v[4:7], off offset:2048
	s_nop 1
	v_mov_b64_e32 v[4:5], v[164:165]
	v_mov_b64_e32 v[6:7], v[166:167]
	v_pk_mul_f32 v[0:1], v[4:5], v[0:1]
	v_pk_mul_f32 v[2:3], v[6:7], v[2:3]
	global_store_dwordx4 v[20:21], v[0:3], off offset:3072
	s_branch .LBB0_683
